# plus: residual-norm part-2 pre-norm/shift/scale parameter loads prefetched three groups ahead
# baseline (speedup 1.0000x reference)
.LBB0_1105:
	s_ashr_i32 s7, s6, 31
	s_lshl_b64 s[40:41], s[6:7], 13
	v_lshl_add_u64 v[2:3], v[36:37], 0, s[40:41]
	global_load_dwordx4 v[10:13], v[2:3], off
	global_load_dwordx4 v[18:21], v[2:3], off offset:1024
	global_load_dwordx4 v[22:25], v[2:3], off offset:2048
	global_load_dwordx4 v[30:33], v[2:3], off offset:3072
	v_add_co_u32_e32 v2, vcc, 0x1000, v2
	s_lshl_b64 s[10:11], s[6:7], 12
	s_nop 0
	v_addc_co_u32_e32 v3, vcc, 0, v3, vcc
	v_lshl_add_u64 v[76:77], v[38:39], 0, s[10:11]
	global_load_dwordx4 v[26:29], v[2:3], off
	global_load_dwordx4 v[14:17], v[2:3], off offset:1024
	global_load_dwordx4 v[6:9], v[2:3], off offset:2048
	s_nop 0
	global_load_dwordx4 v[2:5], v[2:3], off offset:3072
	s_mov_b32 s2, 0x800000
	global_load_dwordx2 v[116:117], v[76:77], off
	global_load_dwordx2 v[118:119], v[76:77], off offset:512
	global_load_dwordx2 v[120:121], v[76:77], off offset:1024
	global_load_dwordx2 v[122:123], v[76:77], off offset:1536
	global_load_dwordx2 v[78:79], v[76:77], off offset:2048
	global_load_dwordx2 v[80:81], v[76:77], off offset:2560
	global_load_dwordx2 v[108:109], v[76:77], off offset:3072
	global_load_dwordx2 v[82:83], v[76:77], off offset:3584
	s_ashr_i32 s24, s6, 12
	s_mul_i32 s58, s24, 0x6000
	s_mul_hi_i32 s7, s24, 0x6000
	v_lshlrev_b32_e32 v43, 2, v42
	v_lshlrev_b32_e32 v45, 2, v44
	v_lshlrev_b32_e32 v47, 2, v46
	v_lshlrev_b32_e32 v49, 2, v48
	v_lshlrev_b32_e32 v53, 2, v52
	v_lshlrev_b32_e32 v57, 2, v56
	v_lshlrev_b32_e32 v61, 2, v60
	s_add_u32 s42, s54, s58
	s_addc_u32 s43, s55, s7
	s_add_u32 s42, s42, 0x4000
	s_addc_u32 s43, s43, 0
	v_lshlrev_b32_e32 v164, 2, v34
	global_load_dwordx4 v[124:127], v164, s[42:43]
	global_load_dwordx4 v[128:131], v[40:41], off
	global_load_dwordx4 v[132:135], v43, s[42:43]
	global_load_dwordx4 v[136:139], v[40:41], off offset:1024
	global_load_dwordx4 v[140:143], v45, s[42:43]
	global_load_dwordx4 v[144:147], v[40:41], off offset:2048
	global_load_dwordx4 v[148:151], v47, s[42:43]
	global_load_dwordx4 v[152:155], v[40:41], off offset:3072
	global_load_dwordx4 v[156:159], v49, s[42:43]
	global_load_dwordx4 v[160:163], v[50:51], off
	s_waitcnt vmcnt(17)
	v_lshlrev_b32_e32 v104, 16, v116
	v_and_b32_e32 v105, 0xffff0000, v116
	v_lshlrev_b32_e32 v106, 16, v117
	v_and_b32_e32 v107, 0xffff0000, v117
	v_mul_f32_e32 v0, v105, v105
	v_fmac_f32_e32 v0, v104, v104
	v_fmac_f32_e32 v0, v106, v106
	v_fmac_f32_e32 v0, v107, v107
	s_waitcnt vmcnt(16)
	v_lshlrev_b32_e32 v100, 16, v118
	v_and_b32_e32 v101, 0xffff0000, v118
	v_lshlrev_b32_e32 v102, 16, v119
	v_and_b32_e32 v103, 0xffff0000, v119
	v_mul_f32_e32 v35, v101, v101
	v_fmac_f32_e32 v35, v100, v100
	v_fmac_f32_e32 v35, v102, v102
	v_fmac_f32_e32 v35, v103, v103
	v_add_f32_e32 v0, v0, v35
	s_waitcnt vmcnt(15)
	v_lshlrev_b32_e32 v96, 16, v120
	v_and_b32_e32 v97, 0xffff0000, v120
	v_lshlrev_b32_e32 v98, 16, v121
	v_and_b32_e32 v99, 0xffff0000, v121
	v_mul_f32_e32 v35, v97, v97
	v_fmac_f32_e32 v35, v96, v96
	v_fmac_f32_e32 v35, v98, v98
	v_fmac_f32_e32 v35, v99, v99
	v_add_f32_e32 v0, v0, v35
	s_waitcnt vmcnt(14)
	v_lshlrev_b32_e32 v92, 16, v122
	v_and_b32_e32 v93, 0xffff0000, v122
	v_lshlrev_b32_e32 v94, 16, v123
	v_and_b32_e32 v95, 0xffff0000, v123
	v_mul_f32_e32 v35, v93, v93
	v_fmac_f32_e32 v35, v92, v92
	v_fmac_f32_e32 v35, v94, v94
	v_fmac_f32_e32 v35, v95, v95
	v_add_f32_e32 v0, v0, v35
	s_waitcnt vmcnt(13)
	v_and_b32_e32 v86, 0xffff0000, v78
	s_waitcnt vmcnt(12)
	v_and_b32_e32 v87, 0xffff0000, v80
	v_lshlrev_b32_e32 v85, 16, v80
	v_lshlrev_b32_e32 v84, 16, v78
	v_lshlrev_b32_e32 v88, 16, v79
	v_and_b32_e32 v90, 0xffff0000, v79
	v_pk_mul_f32 v[78:79], v[86:87], v[86:87]
	v_lshlrev_b32_e32 v89, 16, v81
	v_pk_fma_f32 v[78:79], v[84:85], v[84:85], v[78:79]
	v_and_b32_e32 v91, 0xffff0000, v81
	v_pk_fma_f32 v[78:79], v[88:89], v[88:89], v[78:79]
	s_waitcnt vmcnt(10)
	v_lshlrev_b32_e32 v77, 16, v82
	v_pk_fma_f32 v[78:79], v[90:91], v[90:91], v[78:79]
	v_lshlrev_b32_e32 v76, 16, v108
	v_add_f32_e32 v0, v0, v78
	v_add_f32_e32 v0, v0, v79
	v_and_b32_e32 v79, 0xffff0000, v82
	v_and_b32_e32 v78, 0xffff0000, v108
	v_lshlrev_b32_e32 v80, 16, v109
	v_and_b32_e32 v82, 0xffff0000, v109
	v_pk_mul_f32 v[108:109], v[78:79], v[78:79]
	v_lshlrev_b32_e32 v81, 16, v83
	v_pk_fma_f32 v[108:109], v[76:77], v[76:77], v[108:109]
	v_and_b32_e32 v83, 0xffff0000, v83
	v_pk_fma_f32 v[108:109], v[80:81], v[80:81], v[108:109]
	s_nop 0
	v_pk_fma_f32 v[108:109], v[82:83], v[82:83], v[108:109]
	s_nop 0
	v_add_f32_e32 v0, v0, v108
	v_add_f32_e32 v0, v0, v109
	s_nop 1
	v_add_f32_dpp v0, v0, v0 quad_perm:[1,0,3,2] row_mask:0xf bank_mask:0xf bound_ctrl:1
	s_nop 1
	v_add_f32_dpp v0, v0, v0 quad_perm:[2,3,0,1] row_mask:0xf bank_mask:0xf bound_ctrl:1
	s_nop 1
	v_add_f32_dpp v0, v0, v0 row_ror:4 row_mask:0xf bank_mask:0xf bound_ctrl:1
	s_nop 1
	v_add_f32_dpp v0, v0, v0 row_ror:8 row_mask:0xf bank_mask:0xf bound_ctrl:1
	ds_bpermute_b32 v35, v207, v0
	s_waitcnt lgkmcnt(0)
	v_add_f32_e32 v0, v0, v35
	ds_bpermute_b32 v35, v209, v0
	s_waitcnt lgkmcnt(0)
	v_add_f32_e32 v0, v0, v35
	v_fmamk_f32 v0, v0, 0x3a000000, v166
	v_cmp_gt_f32_e32 vcc, s2, v0
	v_mul_f32_e32 v35, 0x4b800000, v0
	s_add_u32 s2, s54, s58
	v_cndmask_b32_e32 v0, v0, v35, vcc
	v_rsq_f32_e32 v0, v0
	s_addc_u32 s17, s55, s7
	s_add_u32 s42, s2, 0x4000
	s_addc_u32 s43, s17, 0
	v_mul_f32_e32 v35, 0x45800000, v0
	v_cndmask_b32_e32 v0, v0, v35, vcc
	v_lshlrev_b32_e32 v35, 2, v34
	v_pk_mul_f32 v[106:107], v[106:107], v[0:1] op_sel_hi:[1,0]
	v_pk_mul_f32 v[104:105], v[104:105], v[0:1] op_sel_hi:[1,0]
	s_add_u32 s40, s84, s40
	s_addc_u32 s41, s85, s41
	v_pk_mul_f32 v[100:101], v[100:101], v[0:1] op_sel_hi:[1,0]
	v_pk_mul_f32 v[102:103], v[102:103], v[0:1] op_sel_hi:[1,0]
	v_pk_mul_f32 v[96:97], v[96:97], v[0:1] op_sel_hi:[1,0]
	v_pk_mul_f32 v[98:99], v[98:99], v[0:1] op_sel_hi:[1,0]
	v_pk_mul_f32 v[92:93], v[92:93], v[0:1] op_sel_hi:[1,0]
	v_pk_mul_f32 v[94:95], v[94:95], v[0:1] op_sel_hi:[1,0]
	s_andn2_b64 vcc, exec, s[0:1]
	s_waitcnt vmcnt(8)
	v_mov_b32_e32 v108, v124
	v_mov_b32_e32 v109, v125
	v_mov_b32_e32 v110, v126
	v_mov_b32_e32 v111, v127
	v_pk_mul_f32 v[104:105], v[108:109], v[104:105]
	v_pk_mul_f32 v[106:107], v[110:111], v[106:107]
	v_mov_b32_e32 v112, v128
	v_mov_b32_e32 v113, v129
	v_mov_b32_e32 v114, v130
	v_mov_b32_e32 v115, v131
	global_load_dwordx4 v[124:127], v53, s[42:43]
	global_load_dwordx4 v[128:131], v[54:55], off
	v_pk_fma_f32 v[10:11], v[112:113], v[104:105], v[10:11]
	v_pk_fma_f32 v[12:13], v[114:115], v[106:107], v[12:13]
	global_store_dwordx4 v35, v[10:13], s[40:41]
	s_waitcnt vmcnt(9)
	v_mov_b32_e32 v104, v132
	v_mov_b32_e32 v105, v133
	v_mov_b32_e32 v106, v134
	v_mov_b32_e32 v107, v135
	v_pk_mul_f32 v[102:103], v[106:107], v[102:103]
	v_pk_mul_f32 v[100:101], v[104:105], v[100:101]
	v_mov_b32_e32 v108, v136
	v_mov_b32_e32 v109, v137
	v_mov_b32_e32 v110, v138
	v_mov_b32_e32 v111, v139
	global_load_dwordx4 v[132:135], v57, s[42:43]
	global_load_dwordx4 v[136:139], v[58:59], off
	v_pk_fma_f32 v[20:21], v[110:111], v[102:103], v[20:21]
	v_pk_fma_f32 v[18:19], v[108:109], v[100:101], v[18:19]
	global_store_dwordx4 v35, v[18:21], s[40:41] offset:1024
	s_waitcnt vmcnt(10)
	v_mov_b32_e32 v100, v140
	v_mov_b32_e32 v101, v141
	v_mov_b32_e32 v102, v142
	v_mov_b32_e32 v103, v143
	v_pk_mul_f32 v[98:99], v[102:103], v[98:99]
	v_pk_mul_f32 v[96:97], v[100:101], v[96:97]
	v_mov_b32_e32 v104, v144
	v_mov_b32_e32 v105, v145
	v_mov_b32_e32 v106, v146
	v_mov_b32_e32 v107, v147
	global_load_dwordx4 v[140:143], v61, s[42:43]
	global_load_dwordx4 v[144:147], v[62:63], off
	v_pk_fma_f32 v[24:25], v[106:107], v[98:99], v[24:25]
	v_pk_fma_f32 v[22:23], v[104:105], v[96:97], v[22:23]
	global_store_dwordx4 v35, v[22:25], s[40:41] offset:2048
	s_waitcnt vmcnt(11)
	v_mov_b32_e32 v96, v148
	v_mov_b32_e32 v97, v149
	v_mov_b32_e32 v98, v150
	v_mov_b32_e32 v99, v151
	v_pk_mul_f32 v[94:95], v[98:99], v[94:95]
	v_pk_mul_f32 v[92:93], v[96:97], v[92:93]
	v_mov_b32_e32 v100, v152
	v_mov_b32_e32 v101, v153
	v_mov_b32_e32 v102, v154
	v_mov_b32_e32 v103, v155
	v_pk_fma_f32 v[32:33], v[102:103], v[94:95], v[32:33]
	v_pk_fma_f32 v[30:31], v[100:101], v[92:93], v[30:31]
	global_store_dwordx4 v35, v[30:33], s[40:41] offset:3072
	v_mov_b32_e32 v100, v84
	v_mov_b32_e32 v101, v86
	v_mov_b32_e32 v102, v88
	v_mov_b32_e32 v103, v90
	v_pk_mul_f32 v[100:101], v[100:101], v[0:1] op_sel_hi:[1,0]
	v_pk_mul_f32 v[102:103], v[102:103], v[0:1] op_sel_hi:[1,0]
	v_mov_b32_e32 v86, v85
	v_mov_b32_e32 v90, v89
	v_pk_mul_f32 v[84:85], v[86:87], v[0:1] op_sel_hi:[1,0]
	v_pk_mul_f32 v[86:87], v[90:91], v[0:1] op_sel_hi:[1,0]
	s_waitcnt vmcnt(10)
	v_mov_b32_e32 v92, v156
	v_mov_b32_e32 v93, v157
	v_mov_b32_e32 v94, v158
	v_mov_b32_e32 v95, v159
	v_pk_mul_f32 v[94:95], v[94:95], v[102:103]
	v_pk_mul_f32 v[92:93], v[92:93], v[100:101]
	v_mov_b32_e32 v96, v160
	v_mov_b32_e32 v97, v161
	v_mov_b32_e32 v98, v162
	v_mov_b32_e32 v99, v163
	v_pk_fma_f32 v[28:29], v[98:99], v[94:95], v[28:29]
	v_pk_fma_f32 v[26:27], v[96:97], v[92:93], v[26:27]
	global_store_dwordx4 v49, v[26:29], s[40:41]
	s_waitcnt vmcnt(9)
	v_mov_b32_e32 v92, v124
	v_mov_b32_e32 v93, v125
	v_mov_b32_e32 v94, v126
	v_mov_b32_e32 v95, v127
	v_pk_mul_f32 v[86:87], v[94:95], v[86:87]
	v_pk_mul_f32 v[84:85], v[92:93], v[84:85]
	v_mov_b32_e32 v96, v128
	v_mov_b32_e32 v97, v129
	v_mov_b32_e32 v98, v130
	v_mov_b32_e32 v99, v131
	v_pk_fma_f32 v[16:17], v[98:99], v[86:87], v[16:17]
	v_pk_fma_f32 v[14:15], v[96:97], v[84:85], v[14:15]
	global_store_dwordx4 v53, v[14:17], s[40:41]
	v_mov_b32_e32 v92, v76
	v_mov_b32_e32 v93, v78
	v_mov_b32_e32 v94, v80
	v_mov_b32_e32 v95, v82
	v_pk_mul_f32 v[92:93], v[92:93], v[0:1] op_sel_hi:[1,0]
	v_pk_mul_f32 v[94:95], v[94:95], v[0:1] op_sel_hi:[1,0]
	v_mov_b32_e32 v78, v77
	v_mov_b32_e32 v82, v81
	v_pk_mul_f32 v[76:77], v[78:79], v[0:1] op_sel_hi:[1,0]
	v_pk_mul_f32 v[78:79], v[82:83], v[0:1] op_sel_hi:[1,0]
	s_waitcnt vmcnt(7)
	v_mov_b32_e32 v84, v132
	v_mov_b32_e32 v85, v133
	v_mov_b32_e32 v86, v134
	v_mov_b32_e32 v87, v135
	v_pk_mul_f32 v[86:87], v[94:95], v[86:87]
	v_pk_mul_f32 v[84:85], v[92:93], v[84:85]
	v_mov_b32_e32 v88, v136
	v_mov_b32_e32 v89, v137
	v_mov_b32_e32 v90, v138
	v_mov_b32_e32 v91, v139
	v_pk_fma_f32 v[8:9], v[90:91], v[86:87], v[8:9]
	v_pk_fma_f32 v[6:7], v[88:89], v[84:85], v[6:7]
	global_store_dwordx4 v57, v[6:9], s[40:41]
	s_waitcnt vmcnt(5)
	v_mov_b32_e32 v84, v140
	v_mov_b32_e32 v85, v141
	v_mov_b32_e32 v86, v142
	v_mov_b32_e32 v87, v143
	v_pk_mul_f32 v[78:79], v[78:79], v[86:87]
	v_pk_mul_f32 v[76:77], v[76:77], v[84:85]
	v_mov_b32_e32 v88, v144
	v_mov_b32_e32 v89, v145
	v_mov_b32_e32 v90, v146
	v_mov_b32_e32 v91, v147
	v_pk_fma_f32 v[4:5], v[90:91], v[78:79], v[4:5]
	v_pk_fma_f32 v[2:3], v[88:89], v[76:77], v[2:3]
	global_store_dwordx4 v61, v[2:5], s[40:41]
	s_cbranch_vccnz .LBB0_1104
	v_mul_f32_e32 v0, v11, v11
	v_mul_f32_e32 v76, v19, v19
	v_fmac_f32_e32 v0, v10, v10
	v_fmac_f32_e32 v76, v18, v18
	v_fmac_f32_e32 v0, v12, v12
	v_fmac_f32_e32 v76, v20, v20
	v_fmac_f32_e32 v0, v13, v13
	v_fmac_f32_e32 v76, v21, v21
	v_add_f32_e32 v0, v0, v76
	v_mul_f32_e32 v76, v23, v23
	v_fmac_f32_e32 v76, v22, v22
	v_fmac_f32_e32 v76, v24, v24
	v_fmac_f32_e32 v76, v25, v25
	v_add_f32_e32 v0, v76, v0
	v_mul_f32_e32 v76, v31, v31
	v_fmac_f32_e32 v76, v30, v30
	v_fmac_f32_e32 v76, v32, v32
	v_fmac_f32_e32 v76, v33, v33
	v_mov_b32_e32 v78, v15
	v_mov_b32_e32 v79, v27
	v_add_f32_e32 v0, v76, v0
	v_mov_b32_e32 v76, v14
	v_mov_b32_e32 v77, v26
	v_pk_mul_f32 v[78:79], v[78:79], v[78:79]
	s_mov_b32 s2, 0x800000
	v_pk_fma_f32 v[76:77], v[76:77], v[76:77], v[78:79]
	v_mov_b32_e32 v78, v16
	v_mov_b32_e32 v79, v28
	v_pk_fma_f32 v[76:77], v[78:79], v[78:79], v[76:77]
	v_mov_b32_e32 v78, v17
	v_mov_b32_e32 v79, v29
	v_pk_fma_f32 v[76:77], v[78:79], v[78:79], v[76:77]
	v_mov_b32_e32 v78, v3
	v_add_f32_e32 v0, v77, v0
	v_mov_b32_e32 v79, v7
	v_add_f32_e32 v0, v76, v0
	v_mov_b32_e32 v76, v2
	v_mov_b32_e32 v77, v6
	v_pk_mul_f32 v[78:79], v[78:79], v[78:79]
	s_add_u32 s42, s62, s58
	v_pk_fma_f32 v[76:77], v[76:77], v[76:77], v[78:79]
	v_mov_b32_e32 v78, v4
	v_mov_b32_e32 v79, v8
	v_pk_fma_f32 v[76:77], v[78:79], v[78:79], v[76:77]
	v_mov_b32_e32 v78, v5
	v_mov_b32_e32 v79, v9
	v_pk_fma_f32 v[76:77], v[78:79], v[78:79], v[76:77]
	s_addc_u32 s43, s63, s7
	v_add_f32_e32 v0, v77, v0
	v_add_f32_e32 v0, v76, v0
	s_add_u32 s40, s42, 0x2000
	s_addc_u32 s41, s43, 0
	global_load_dwordx4 v[124:127], v[64:65], off
	global_load_dwordx4 v[128:131], v35, s[42:43]
	global_load_dwordx4 v[132:135], v35, s[40:41]
	global_load_dwordx4 v[136:139], v[64:65], off offset:1024
	global_load_dwordx4 v[140:143], v35, s[42:43] offset:1024
	global_load_dwordx4 v[144:147], v43, s[40:41]
	global_load_dwordx4 v[148:151], v[64:65], off offset:2048
	global_load_dwordx4 v[152:155], v35, s[42:43] offset:2048
	global_load_dwordx4 v[156:159], v45, s[40:41]
	v_add_f32_dpp v0, v0, v0 quad_perm:[1,0,3,2] row_mask:0xf bank_mask:0xf bound_ctrl:1
	s_nop 1
	v_add_f32_dpp v0, v0, v0 quad_perm:[2,3,0,1] row_mask:0xf bank_mask:0xf bound_ctrl:1
	s_nop 1
	v_add_f32_dpp v0, v0, v0 row_ror:4 row_mask:0xf bank_mask:0xf bound_ctrl:1
	s_nop 1
	v_add_f32_dpp v0, v0, v0 row_ror:8 row_mask:0xf bank_mask:0xf bound_ctrl:1
	ds_bpermute_b32 v76, v207, v0
	s_waitcnt lgkmcnt(0)
	v_add_f32_e32 v0, v0, v76
	ds_bpermute_b32 v76, v209, v0
	s_waitcnt lgkmcnt(0)
	v_add_f32_e32 v0, v0, v76
	v_fmamk_f32 v0, v0, 0x3a000000, v166
	v_cmp_gt_f32_e32 vcc, s2, v0
	v_mul_f32_e32 v76, 0x4b800000, v0
	s_nop 0
	v_cndmask_b32_e32 v0, v0, v76, vcc
	v_rsq_f32_e32 v0, v0
	s_nop 0
	v_mul_f32_e32 v76, 0x45800000, v0
	v_cndmask_b32_e32 v0, v0, v76, vcc
	v_pk_mul_f32 v[12:13], v[12:13], v[0:1] op_sel_hi:[1,0]
	v_pk_mul_f32 v[10:11], v[10:11], v[0:1] op_sel_hi:[1,0]
	v_pk_mul_f32 v[18:19], v[18:19], v[0:1] op_sel_hi:[1,0]
	v_pk_mul_f32 v[22:23], v[22:23], v[0:1] op_sel_hi:[1,0]
	v_pk_mul_f32 v[30:31], v[30:31], v[0:1] op_sel_hi:[1,0]
	v_pk_mul_f32 v[26:27], v[26:27], v[0:1] op_sel_hi:[1,0]
	v_pk_mul_f32 v[14:15], v[14:15], v[0:1] op_sel_hi:[1,0]
	v_pk_mul_f32 v[8:9], v[8:9], v[0:1] op_sel_hi:[1,0]
	v_pk_mul_f32 v[6:7], v[6:7], v[0:1] op_sel_hi:[1,0]
	v_pk_mul_f32 v[4:5], v[4:5], v[0:1] op_sel_hi:[1,0]
	v_pk_mul_f32 v[2:3], v[2:3], v[0:1] op_sel_hi:[1,0]
	s_waitcnt vmcnt(6)
	v_mov_b32_e32 v76, v124
	v_mov_b32_e32 v77, v125
	v_mov_b32_e32 v78, v126
	v_mov_b32_e32 v79, v127
	v_pk_mul_f32 v[10:11], v[76:77], v[10:11]
	v_pk_mul_f32 v[12:13], v[78:79], v[12:13]
	v_mov_b32_e32 v80, v128
	v_mov_b32_e32 v81, v129
	v_mov_b32_e32 v82, v130
	v_mov_b32_e32 v83, v131
	v_mov_b32_e32 v84, v132
	v_mov_b32_e32 v85, v133
	v_mov_b32_e32 v86, v134
	v_mov_b32_e32 v87, v135
	global_load_dwordx4 v[124:127], v[64:65], off offset:3072
	global_load_dwordx4 v[128:131], v35, s[42:43] offset:3072
	global_load_dwordx4 v[132:135], v47, s[40:41]
	v_pk_add_f32 v[76:77], v[86:87], 1.0 op_sel_hi:[1,0]
	v_pk_add_f32 v[78:79], v[84:85], 1.0 op_sel_hi:[1,0]
	v_pk_fma_f32 v[12:13], v[76:77], v[12:13], v[82:83]
	v_pk_fma_f32 v[10:11], v[78:79], v[10:11], v[80:81]
	s_nop 0
	v_cvt_pk_bf16_f32 v10, v10, v11
	v_cvt_pk_bf16_f32 v11, v12, v13
	v_lshl_add_u64 v[12:13], v[74:75], 0, s[10:11]
	global_store_dwordx2 v[12:13], v[10:11], off
	v_pk_mul_f32 v[10:11], v[20:21], v[0:1] op_sel_hi:[1,0]
	s_waitcnt vmcnt(7)
	v_mov_b32_e32 v76, v136
	v_mov_b32_e32 v77, v137
	v_mov_b32_e32 v78, v138
	v_mov_b32_e32 v79, v139
	v_pk_mul_f32 v[18:19], v[76:77], v[18:19]
	v_pk_mul_f32 v[10:11], v[78:79], v[10:11]
	v_mov_b32_e32 v80, v140
	v_mov_b32_e32 v81, v141
	v_mov_b32_e32 v82, v142
	v_mov_b32_e32 v83, v143
	v_mov_b32_e32 v84, v144
	v_mov_b32_e32 v85, v145
	v_mov_b32_e32 v86, v146
	v_mov_b32_e32 v87, v147
	global_load_dwordx4 v[136:139], v[66:67], off
	global_load_dwordx4 v[140:143], v49, s[42:43]
	global_load_dwordx4 v[144:147], v49, s[40:41]
	v_pk_add_f32 v[20:21], v[86:87], 1.0 op_sel_hi:[1,0]
	v_pk_add_f32 v[76:77], v[84:85], 1.0 op_sel_hi:[1,0]
	v_pk_fma_f32 v[10:11], v[20:21], v[10:11], v[82:83]
	v_pk_fma_f32 v[18:19], v[76:77], v[18:19], v[80:81]
	s_nop 0
	v_cvt_pk_bf16_f32 v18, v18, v19
	v_cvt_pk_bf16_f32 v19, v10, v11
	global_store_dwordx2 v[12:13], v[18:19], off offset:512
	s_nop 0
	v_pk_mul_f32 v[10:11], v[24:25], v[0:1] op_sel_hi:[1,0]
	s_waitcnt vmcnt(8)
	v_mov_b32_e32 v18, v148
	v_mov_b32_e32 v19, v149
	v_mov_b32_e32 v20, v150
	v_mov_b32_e32 v21, v151
	v_pk_mul_f32 v[18:19], v[18:19], v[22:23]
	v_pk_mul_f32 v[10:11], v[20:21], v[10:11]
	v_mov_b32_e32 v76, v152
	v_mov_b32_e32 v77, v153
	v_mov_b32_e32 v78, v154
	v_mov_b32_e32 v79, v155
	v_mov_b32_e32 v80, v156
	v_mov_b32_e32 v81, v157
	v_mov_b32_e32 v82, v158
	v_mov_b32_e32 v83, v159
	global_load_dwordx4 v[148:151], v[68:69], off
	global_load_dwordx4 v[152:155], v53, s[42:43]
	global_load_dwordx4 v[156:159], v53, s[40:41]
	v_pk_add_f32 v[20:21], v[82:83], 1.0 op_sel_hi:[1,0]
	v_pk_add_f32 v[22:23], v[80:81], 1.0 op_sel_hi:[1,0]
	v_pk_fma_f32 v[10:11], v[20:21], v[10:11], v[78:79]
	v_pk_fma_f32 v[18:19], v[22:23], v[18:19], v[76:77]
	s_nop 0
	v_cvt_pk_bf16_f32 v18, v18, v19
	v_cvt_pk_bf16_f32 v19, v10, v11
	global_store_dwordx2 v[12:13], v[18:19], off offset:1024
	s_nop 0
	v_pk_mul_f32 v[10:11], v[32:33], v[0:1] op_sel_hi:[1,0]
	s_waitcnt vmcnt(9)
	v_mov_b32_e32 v18, v124
	v_mov_b32_e32 v19, v125
	v_mov_b32_e32 v20, v126
	v_mov_b32_e32 v21, v127
	v_pk_mul_f32 v[18:19], v[30:31], v[18:19]
	v_pk_mul_f32 v[10:11], v[10:11], v[20:21]
	v_mov_b32_e32 v22, v128
	v_mov_b32_e32 v23, v129
	v_mov_b32_e32 v24, v130
	v_mov_b32_e32 v25, v131
	v_mov_b32_e32 v76, v132
	v_mov_b32_e32 v77, v133
	v_mov_b32_e32 v78, v134
	v_mov_b32_e32 v79, v135
	global_load_dwordx4 v[124:127], v[70:71], off
	global_load_dwordx4 v[128:131], v57, s[42:43]
	global_load_dwordx4 v[132:135], v57, s[40:41]
	v_pk_add_f32 v[20:21], v[78:79], 1.0 op_sel_hi:[1,0]
	v_pk_add_f32 v[30:31], v[76:77], 1.0 op_sel_hi:[1,0]
	v_pk_fma_f32 v[10:11], v[10:11], v[20:21], v[24:25]
	v_pk_fma_f32 v[18:19], v[18:19], v[30:31], v[22:23]
	s_nop 0
	v_cvt_pk_bf16_f32 v18, v18, v19
	v_cvt_pk_bf16_f32 v19, v10, v11
	global_store_dwordx2 v[12:13], v[18:19], off offset:1536
	s_nop 0
	v_pk_mul_f32 v[10:11], v[28:29], v[0:1] op_sel_hi:[1,0]
	s_waitcnt vmcnt(9)
	v_mov_b32_e32 v18, v136
	v_mov_b32_e32 v19, v137
	v_mov_b32_e32 v20, v138
	v_mov_b32_e32 v21, v139
	v_pk_mul_f32 v[18:19], v[26:27], v[18:19]
	v_pk_mul_f32 v[10:11], v[10:11], v[20:21]
	v_mov_b32_e32 v22, v140
	v_mov_b32_e32 v23, v141
	v_mov_b32_e32 v24, v142
	v_mov_b32_e32 v25, v143
	v_mov_b32_e32 v30, v144
	v_mov_b32_e32 v31, v145
	v_mov_b32_e32 v32, v146
	v_mov_b32_e32 v33, v147
	global_load_dwordx4 v[136:139], v[72:73], off
	global_load_dwordx4 v[140:143], v61, s[42:43]
	global_load_dwordx4 v[144:147], v61, s[40:41]
	v_pk_add_f32 v[20:21], v[32:33], 1.0 op_sel_hi:[1,0]
	v_pk_add_f32 v[26:27], v[30:31], 1.0 op_sel_hi:[1,0]
	v_pk_fma_f32 v[10:11], v[10:11], v[20:21], v[24:25]
	v_pk_fma_f32 v[18:19], v[18:19], v[26:27], v[22:23]
	s_nop 0
	v_cvt_pk_bf16_f32 v18, v18, v19
	v_cvt_pk_bf16_f32 v19, v10, v11
	global_store_dwordx2 v[12:13], v[18:19], off offset:2048
	s_nop 0
	v_pk_mul_f32 v[10:11], v[16:17], v[0:1] op_sel_hi:[1,0]
	s_waitcnt vmcnt(9)
	v_mov_b32_e32 v18, v148
	v_mov_b32_e32 v19, v149
	v_mov_b32_e32 v20, v150
	v_mov_b32_e32 v21, v151
	v_pk_mul_f32 v[14:15], v[14:15], v[18:19]
	v_pk_mul_f32 v[10:11], v[10:11], v[20:21]
	v_mov_b32_e32 v22, v152
	v_mov_b32_e32 v23, v153
	v_mov_b32_e32 v24, v154
	v_mov_b32_e32 v25, v155
	v_mov_b32_e32 v26, v156
	v_mov_b32_e32 v27, v157
	v_mov_b32_e32 v28, v158
	v_mov_b32_e32 v29, v159
	v_pk_add_f32 v[16:17], v[28:29], 1.0 op_sel_hi:[1,0]
	v_pk_add_f32 v[18:19], v[26:27], 1.0 op_sel_hi:[1,0]
	v_pk_fma_f32 v[10:11], v[10:11], v[16:17], v[24:25]
	v_pk_fma_f32 v[14:15], v[14:15], v[18:19], v[22:23]
	s_nop 0
	v_cvt_pk_bf16_f32 v14, v14, v15
	v_cvt_pk_bf16_f32 v15, v10, v11
	global_store_dwordx2 v[12:13], v[14:15], off offset:2560
	s_nop 0
	s_waitcnt vmcnt(6)
	v_mov_b32_e32 v14, v124
	v_mov_b32_e32 v15, v125
	v_mov_b32_e32 v16, v126
	v_mov_b32_e32 v17, v127
	v_pk_mul_f32 v[6:7], v[6:7], v[14:15]
	v_pk_mul_f32 v[8:9], v[8:9], v[16:17]
	v_mov_b32_e32 v18, v128
	v_mov_b32_e32 v19, v129
	v_mov_b32_e32 v20, v130
	v_mov_b32_e32 v21, v131
	v_mov_b32_e32 v22, v132
	v_mov_b32_e32 v23, v133
	v_mov_b32_e32 v24, v134
	v_mov_b32_e32 v25, v135
	v_pk_add_f32 v[10:11], v[24:25], 1.0 op_sel_hi:[1,0]
	v_pk_add_f32 v[14:15], v[22:23], 1.0 op_sel_hi:[1,0]
	v_pk_fma_f32 v[8:9], v[8:9], v[10:11], v[20:21]
	v_pk_fma_f32 v[6:7], v[6:7], v[14:15], v[18:19]
	s_nop 0
	v_cvt_pk_bf16_f32 v6, v6, v7
	v_cvt_pk_bf16_f32 v7, v8, v9
	global_store_dwordx2 v[12:13], v[6:7], off offset:3072
	s_nop 0
	s_waitcnt vmcnt(3)
	v_mov_b32_e32 v6, v136
	v_mov_b32_e32 v7, v137
	v_mov_b32_e32 v8, v138
	v_mov_b32_e32 v9, v139
	v_pk_mul_f32 v[2:3], v[2:3], v[6:7]
	v_pk_mul_f32 v[4:5], v[4:5], v[8:9]
	v_mov_b32_e32 v14, v140
	v_mov_b32_e32 v15, v141
	v_mov_b32_e32 v16, v142
	v_mov_b32_e32 v17, v143
	v_mov_b32_e32 v18, v144
	v_mov_b32_e32 v19, v145
	v_mov_b32_e32 v20, v146
	v_mov_b32_e32 v21, v147
	v_pk_add_f32 v[6:7], v[20:21], 1.0 op_sel_hi:[1,0]
	v_pk_add_f32 v[8:9], v[18:19], 1.0 op_sel_hi:[1,0]
	v_pk_fma_f32 v[4:5], v[4:5], v[6:7], v[16:17]
	v_pk_fma_f32 v[2:3], v[2:3], v[8:9], v[14:15]
	s_nop 0
	v_cvt_pk_bf16_f32 v2, v2, v3
	v_cvt_pk_bf16_f32 v3, v4, v5
	global_store_dwordx2 v[12:13], v[2:3], off offset:3584
	s_branch .LBB0_1104
